# norm split-K partial fold: 32 loads issued together then summed in the same order (was serialized load-wait-add chain)
# speedup vs baseline: 1.0131x; 1.0131x over previous
.LBB0_772:
	v_readlane_b32 s0, v254, 33
	s_waitcnt lgkmcnt(0)
	flat_load_dwordx4 v[16:19], v[48:49]
	flat_load_dwordx4 v[24:27], v[48:49] offset:16
	flat_load_dwordx4 v[12:15], v[48:49] offset:2048
	flat_load_dwordx4 v[28:31], v[48:49] offset:2064
	v_add_u32_e32 v33, s0, v32
	s_mov_b32 s0, 0x8800
	v_cmp_gt_i32_e32 vcc, s0, v33
	s_movk_i32 s0, 0x7fff
	v_readlane_b32 s1, v254, 34
	v_cndmask_b32_e32 v0, v32, v33, vcc
	v_ashrrev_i32_e32 v1, 31, v0
	v_lshlrev_b64 v[0:1], 12, v[0:1]
	v_lshl_add_u64 v[20:21], v[36:37], 0, v[0:1]
	flat_load_dwordx4 v[4:7], v[20:21]
	flat_load_dwordx4 v[8:11], v[20:21] offset:16
	flat_load_dwordx4 v[0:3], v[20:21] offset:2048
	s_nop 0
	flat_load_dwordx4 v[20:23], v[20:21] offset:2064
	v_cmp_lt_i32_e32 vcc, s0, v32
	s_and_b64 s[48:49], s[46:47], vcc
	v_lshlrev_b32_e32 v50, 2, v34
	s_and_saveexec_b64 s[0:1], s[48:49]
	s_cbranch_execz .LBB0_774
	v_lshlrev_b64 v[52:53], 2, v[176:177]
	v_lshl_add_u64 v[54:55], s[2:3], 0, v[52:53]
	v_mov_b32_e32 v51, v177
	v_lshl_add_u64 v[54:55], v[54:55], 0, v[50:51]
	s_brev_b32 s48, 31
	s_mov_b32 s49, -1
	v_lshl_add_u64 v[56:57], v[54:55], 0, s[48:49]
	s_mov_b32 s48, 0x800000
	s_mov_b32 s49, 0
	v_lshl_add_u64 v[64:65], v[56:57], 0, s[48:49]
	global_load_dwordx4 v[112:115], v[56:57], off
	global_load_dwordx4 v[116:119], v[56:57], off offset:16
	global_load_dwordx4 v[120:123], v[56:57], off offset:2048
	global_load_dwordx4 v[124:127], v[56:57], off offset:2064
	v_lshl_add_u64 v[56:57], v[64:65], 0, s[48:49]
	global_load_dwordx4 v[128:131], v[64:65], off
	global_load_dwordx4 v[132:135], v[64:65], off offset:16
	global_load_dwordx4 v[136:139], v[64:65], off offset:2048
	global_load_dwordx4 v[140:143], v[64:65], off offset:2064
	v_lshl_add_u64 v[64:65], v[56:57], 0, s[48:49]
	global_load_dwordx4 v[144:147], v[56:57], off
	global_load_dwordx4 v[148:151], v[56:57], off offset:16
	global_load_dwordx4 v[152:155], v[56:57], off offset:2048
	global_load_dwordx4 v[156:159], v[56:57], off offset:2064
	v_lshl_add_u64 v[56:57], v[64:65], 0, s[48:49]
	global_load_dwordx4 v[160:163], v[64:65], off
	global_load_dwordx4 v[164:167], v[64:65], off offset:16
	global_load_dwordx4 v[168:171], v[64:65], off offset:2048
	global_load_dwordx4 v[172:175], v[64:65], off offset:2064
	v_lshl_add_u64 v[64:65], v[56:57], 0, s[48:49]
	global_load_dwordx4 v[68:71], v[56:57], off
	global_load_dwordx4 v[72:75], v[56:57], off offset:16
	global_load_dwordx4 v[76:79], v[56:57], off offset:2048
	global_load_dwordx4 v[80:83], v[56:57], off offset:2064
	v_lshl_add_u64 v[56:57], v[64:65], 0, s[48:49]
	global_load_dwordx4 v[88:91], v[64:65], off
	global_load_dwordx4 v[92:95], v[64:65], off offset:16
	global_load_dwordx4 v[96:99], v[64:65], off offset:2048
	global_load_dwordx4 v[100:103], v[64:65], off offset:2064
	v_lshl_add_u64 v[64:65], v[56:57], 0, s[48:49]
	global_load_dwordx4 v[224:227], v[56:57], off
	global_load_dwordx4 v[228:231], v[56:57], off offset:16
	global_load_dwordx4 v[232:235], v[56:57], off offset:2048
	global_load_dwordx4 v[236:239], v[56:57], off offset:2064
	global_load_dwordx4 v[240:243], v[64:65], off
	global_load_dwordx4 v[244:247], v[64:65], off offset:16
	global_load_dwordx4 v[192:195], v[64:65], off offset:2048
	global_load_dwordx4 v[196:199], v[64:65], off offset:2064
	v_lshl_add_u64 v[52:53], v[36:37], 0, v[52:53]
	s_waitcnt vmcnt(0) lgkmcnt(0)
	v_pk_add_f32 v[16:17], v[16:17], v[112:113]
	v_pk_add_f32 v[18:19], v[18:19], v[114:115]
	v_pk_add_f32 v[24:25], v[24:25], v[116:117]
	v_pk_add_f32 v[26:27], v[26:27], v[118:119]
	v_pk_add_f32 v[12:13], v[12:13], v[120:121]
	v_pk_add_f32 v[14:15], v[14:15], v[122:123]
	v_pk_add_f32 v[28:29], v[28:29], v[124:125]
	v_pk_add_f32 v[30:31], v[30:31], v[126:127]
	v_pk_add_f32 v[16:17], v[16:17], v[128:129]
	v_pk_add_f32 v[18:19], v[18:19], v[130:131]
	v_pk_add_f32 v[24:25], v[24:25], v[132:133]
	v_pk_add_f32 v[26:27], v[26:27], v[134:135]
	v_pk_add_f32 v[12:13], v[12:13], v[136:137]
	v_pk_add_f32 v[14:15], v[14:15], v[138:139]
	v_pk_add_f32 v[28:29], v[28:29], v[140:141]
	v_pk_add_f32 v[30:31], v[30:31], v[142:143]
	v_pk_add_f32 v[16:17], v[16:17], v[144:145]
	v_pk_add_f32 v[18:19], v[18:19], v[146:147]
	v_pk_add_f32 v[24:25], v[24:25], v[148:149]
	v_pk_add_f32 v[26:27], v[26:27], v[150:151]
	v_pk_add_f32 v[12:13], v[12:13], v[152:153]
	v_pk_add_f32 v[14:15], v[14:15], v[154:155]
	v_pk_add_f32 v[28:29], v[28:29], v[156:157]
	v_pk_add_f32 v[30:31], v[30:31], v[158:159]
	v_pk_add_f32 v[16:17], v[16:17], v[160:161]
	v_pk_add_f32 v[18:19], v[18:19], v[162:163]
	v_pk_add_f32 v[24:25], v[24:25], v[164:165]
	v_pk_add_f32 v[26:27], v[26:27], v[166:167]
	v_pk_add_f32 v[12:13], v[12:13], v[168:169]
	v_pk_add_f32 v[14:15], v[14:15], v[170:171]
	v_pk_add_f32 v[28:29], v[28:29], v[172:173]
	v_pk_add_f32 v[30:31], v[30:31], v[174:175]
	v_pk_add_f32 v[16:17], v[16:17], v[68:69]
	v_pk_add_f32 v[18:19], v[18:19], v[70:71]
	v_pk_add_f32 v[24:25], v[24:25], v[72:73]
	v_pk_add_f32 v[26:27], v[26:27], v[74:75]
	v_pk_add_f32 v[12:13], v[12:13], v[76:77]
	v_pk_add_f32 v[14:15], v[14:15], v[78:79]
	v_pk_add_f32 v[28:29], v[28:29], v[80:81]
	v_pk_add_f32 v[30:31], v[30:31], v[82:83]
	v_pk_add_f32 v[16:17], v[16:17], v[88:89]
	v_pk_add_f32 v[18:19], v[18:19], v[90:91]
	v_pk_add_f32 v[24:25], v[24:25], v[92:93]
	v_pk_add_f32 v[26:27], v[26:27], v[94:95]
	v_pk_add_f32 v[12:13], v[12:13], v[96:97]
	v_pk_add_f32 v[14:15], v[14:15], v[98:99]
	v_pk_add_f32 v[28:29], v[28:29], v[100:101]
	v_pk_add_f32 v[30:31], v[30:31], v[102:103]
	v_pk_add_f32 v[16:17], v[16:17], v[224:225]
	v_pk_add_f32 v[18:19], v[18:19], v[226:227]
	v_pk_add_f32 v[24:25], v[24:25], v[228:229]
	v_pk_add_f32 v[26:27], v[26:27], v[230:231]
	v_pk_add_f32 v[12:13], v[12:13], v[232:233]
	v_pk_add_f32 v[14:15], v[14:15], v[234:235]
	v_pk_add_f32 v[28:29], v[28:29], v[236:237]
	v_pk_add_f32 v[30:31], v[30:31], v[238:239]
	v_pk_add_f32 v[16:17], v[16:17], v[240:241]
	v_pk_add_f32 v[18:19], v[18:19], v[242:243]
	v_pk_add_f32 v[24:25], v[24:25], v[244:245]
	v_pk_add_f32 v[26:27], v[26:27], v[246:247]
	v_pk_add_f32 v[12:13], v[12:13], v[192:193]
	v_pk_add_f32 v[14:15], v[14:15], v[194:195]
	v_pk_add_f32 v[28:29], v[28:29], v[196:197]
	v_pk_add_f32 v[30:31], v[30:31], v[198:199]
	global_store_dwordx4 v[52:53], v[16:19], off
	global_store_dwordx4 v[52:53], v[24:27], off offset:16
	global_store_dwordx4 v[52:53], v[12:15], off offset:2048
	global_store_dwordx4 v[52:53], v[28:31], off offset:2064

.LBB0_975:
	v_readlane_b32 s42, v254, 33
	s_mov_b32 s30, 0x8800
	flat_load_dwordx4 v[28:31], v[50:51]
	flat_load_dwordx4 v[24:27], v[50:51] offset:16
	flat_load_dwordx4 v[16:19], v[50:51] offset:2048
	flat_load_dwordx4 v[20:23], v[50:51] offset:2064
	v_add_u32_e32 v33, s42, v32
	v_cmp_gt_i32_e32 vcc, s30, v33
	s_movk_i32 s30, 0x7fff
	v_lshlrev_b32_e32 v52, 2, v34
	v_cndmask_b32_e32 v0, v32, v33, vcc
	v_ashrrev_i32_e32 v1, 31, v0
	v_lshlrev_b64 v[0:1], 12, v[0:1]
	v_lshl_add_u64 v[4:5], v[36:37], 0, v[0:1]
	flat_load_dwordx4 v[12:15], v[4:5]
	flat_load_dwordx4 v[8:11], v[4:5] offset:16
	flat_load_dwordx4 v[0:3], v[4:5] offset:2048
	s_nop 0
	flat_load_dwordx4 v[4:7], v[4:5] offset:2064
	v_cmp_lt_i32_e32 vcc, s30, v32
	v_readlane_b32 s43, v254, 34
	s_and_saveexec_b64 s[44:45], vcc
	s_cbranch_execz .LBB0_977
	v_lshlrev_b64 v[54:55], 2, v[176:177]
	v_lshl_add_u64 v[56:57], s[2:3], 0, v[54:55]
	v_mov_b32_e32 v53, v177
	v_lshl_add_u64 v[56:57], v[56:57], 0, v[52:53]
	s_brev_b32 s42, 31
	s_mov_b32 s43, -1
	v_lshl_add_u64 v[58:59], v[56:57], 0, s[42:43]
	s_mov_b32 s42, 0x800000
	s_mov_b32 s43, 0
	v_lshl_add_u64 v[60:61], v[58:59], 0, s[42:43]
	global_load_dwordx4 v[112:115], v[58:59], off
	global_load_dwordx4 v[116:119], v[58:59], off offset:16
	global_load_dwordx4 v[120:123], v[58:59], off offset:2048
	global_load_dwordx4 v[124:127], v[58:59], off offset:2064
	v_lshl_add_u64 v[58:59], v[60:61], 0, s[42:43]
	global_load_dwordx4 v[128:131], v[60:61], off
	global_load_dwordx4 v[132:135], v[60:61], off offset:16
	global_load_dwordx4 v[136:139], v[60:61], off offset:2048
	global_load_dwordx4 v[140:143], v[60:61], off offset:2064
	v_lshl_add_u64 v[60:61], v[58:59], 0, s[42:43]
	global_load_dwordx4 v[144:147], v[58:59], off
	global_load_dwordx4 v[148:151], v[58:59], off offset:16
	global_load_dwordx4 v[152:155], v[58:59], off offset:2048
	global_load_dwordx4 v[156:159], v[58:59], off offset:2064
	v_lshl_add_u64 v[58:59], v[60:61], 0, s[42:43]
	global_load_dwordx4 v[160:163], v[60:61], off
	global_load_dwordx4 v[164:167], v[60:61], off offset:16
	global_load_dwordx4 v[168:171], v[60:61], off offset:2048
	global_load_dwordx4 v[172:175], v[60:61], off offset:2064
	v_lshl_add_u64 v[60:61], v[58:59], 0, s[42:43]
	global_load_dwordx4 v[68:71], v[58:59], off
	global_load_dwordx4 v[72:75], v[58:59], off offset:16
	global_load_dwordx4 v[76:79], v[58:59], off offset:2048
	global_load_dwordx4 v[80:83], v[58:59], off offset:2064
	v_lshl_add_u64 v[58:59], v[60:61], 0, s[42:43]
	global_load_dwordx4 v[88:91], v[60:61], off
	global_load_dwordx4 v[92:95], v[60:61], off offset:16
	global_load_dwordx4 v[96:99], v[60:61], off offset:2048
	global_load_dwordx4 v[100:103], v[60:61], off offset:2064
	v_lshl_add_u64 v[60:61], v[58:59], 0, s[42:43]
	global_load_dwordx4 v[224:227], v[58:59], off
	global_load_dwordx4 v[228:231], v[58:59], off offset:16
	global_load_dwordx4 v[232:235], v[58:59], off offset:2048
	global_load_dwordx4 v[236:239], v[58:59], off offset:2064
	global_load_dwordx4 v[240:243], v[60:61], off
	global_load_dwordx4 v[244:247], v[60:61], off offset:16
	global_load_dwordx4 v[192:195], v[60:61], off offset:2048
	global_load_dwordx4 v[196:199], v[60:61], off offset:2064
	v_lshl_add_u64 v[54:55], v[36:37], 0, v[54:55]
	s_waitcnt vmcnt(0) lgkmcnt(0)
	v_pk_add_f32 v[28:29], v[28:29], v[112:113]
	v_pk_add_f32 v[30:31], v[30:31], v[114:115]
	v_pk_add_f32 v[24:25], v[24:25], v[116:117]
	v_pk_add_f32 v[26:27], v[26:27], v[118:119]
	v_pk_add_f32 v[16:17], v[16:17], v[120:121]
	v_pk_add_f32 v[18:19], v[18:19], v[122:123]
	v_pk_add_f32 v[20:21], v[20:21], v[124:125]
	v_pk_add_f32 v[22:23], v[22:23], v[126:127]
	v_pk_add_f32 v[28:29], v[28:29], v[128:129]
	v_pk_add_f32 v[30:31], v[30:31], v[130:131]
	v_pk_add_f32 v[24:25], v[24:25], v[132:133]
	v_pk_add_f32 v[26:27], v[26:27], v[134:135]
	v_pk_add_f32 v[16:17], v[16:17], v[136:137]
	v_pk_add_f32 v[18:19], v[18:19], v[138:139]
	v_pk_add_f32 v[20:21], v[20:21], v[140:141]
	v_pk_add_f32 v[22:23], v[22:23], v[142:143]
	v_pk_add_f32 v[28:29], v[28:29], v[144:145]
	v_pk_add_f32 v[30:31], v[30:31], v[146:147]
	v_pk_add_f32 v[24:25], v[24:25], v[148:149]
	v_pk_add_f32 v[26:27], v[26:27], v[150:151]
	v_pk_add_f32 v[16:17], v[16:17], v[152:153]
	v_pk_add_f32 v[18:19], v[18:19], v[154:155]
	v_pk_add_f32 v[20:21], v[20:21], v[156:157]
	v_pk_add_f32 v[22:23], v[22:23], v[158:159]
	v_pk_add_f32 v[28:29], v[28:29], v[160:161]
	v_pk_add_f32 v[30:31], v[30:31], v[162:163]
	v_pk_add_f32 v[24:25], v[24:25], v[164:165]
	v_pk_add_f32 v[26:27], v[26:27], v[166:167]
	v_pk_add_f32 v[16:17], v[16:17], v[168:169]
	v_pk_add_f32 v[18:19], v[18:19], v[170:171]
	v_pk_add_f32 v[20:21], v[20:21], v[172:173]
	v_pk_add_f32 v[22:23], v[22:23], v[174:175]
	v_pk_add_f32 v[28:29], v[28:29], v[68:69]
	v_pk_add_f32 v[30:31], v[30:31], v[70:71]
	v_pk_add_f32 v[24:25], v[24:25], v[72:73]
	v_pk_add_f32 v[26:27], v[26:27], v[74:75]
	v_pk_add_f32 v[16:17], v[16:17], v[76:77]
	v_pk_add_f32 v[18:19], v[18:19], v[78:79]
	v_pk_add_f32 v[20:21], v[20:21], v[80:81]
	v_pk_add_f32 v[22:23], v[22:23], v[82:83]
	v_pk_add_f32 v[28:29], v[28:29], v[88:89]
	v_pk_add_f32 v[30:31], v[30:31], v[90:91]
	v_pk_add_f32 v[24:25], v[24:25], v[92:93]
	v_pk_add_f32 v[26:27], v[26:27], v[94:95]
	v_pk_add_f32 v[16:17], v[16:17], v[96:97]
	v_pk_add_f32 v[18:19], v[18:19], v[98:99]
	v_pk_add_f32 v[20:21], v[20:21], v[100:101]
	v_pk_add_f32 v[22:23], v[22:23], v[102:103]
	v_pk_add_f32 v[28:29], v[28:29], v[224:225]
	v_pk_add_f32 v[30:31], v[30:31], v[226:227]
	v_pk_add_f32 v[24:25], v[24:25], v[228:229]
	v_pk_add_f32 v[26:27], v[26:27], v[230:231]
	v_pk_add_f32 v[16:17], v[16:17], v[232:233]
	v_pk_add_f32 v[18:19], v[18:19], v[234:235]
	v_pk_add_f32 v[20:21], v[20:21], v[236:237]
	v_pk_add_f32 v[22:23], v[22:23], v[238:239]
	v_pk_add_f32 v[28:29], v[28:29], v[240:241]
	v_pk_add_f32 v[30:31], v[30:31], v[242:243]
	v_pk_add_f32 v[24:25], v[24:25], v[244:245]
	v_pk_add_f32 v[26:27], v[26:27], v[246:247]
	v_pk_add_f32 v[16:17], v[16:17], v[192:193]
	v_pk_add_f32 v[18:19], v[18:19], v[194:195]
	v_pk_add_f32 v[20:21], v[20:21], v[196:197]
	v_pk_add_f32 v[22:23], v[22:23], v[198:199]
	global_store_dwordx4 v[54:55], v[28:31], off
	global_store_dwordx4 v[54:55], v[24:27], off offset:16
	global_store_dwordx4 v[54:55], v[16:19], off offset:2048
	global_store_dwordx4 v[54:55], v[20:23], off offset:2064

.LBB0_2538:
	v_readlane_b32 s40, v254, 33
	s_mov_b32 s30, 0x8800
	flat_load_dwordx4 v[28:31], v[50:51]
	flat_load_dwordx4 v[24:27], v[50:51] offset:16
	flat_load_dwordx4 v[16:19], v[50:51] offset:2048
	flat_load_dwordx4 v[20:23], v[50:51] offset:2064
	v_add_u32_e32 v33, s40, v32
	v_cmp_gt_i32_e32 vcc, s30, v33
	s_movk_i32 s30, 0x7fff
	v_lshlrev_b32_e32 v52, 2, v34
	v_cndmask_b32_e32 v0, v32, v33, vcc
	v_ashrrev_i32_e32 v1, 31, v0
	v_lshlrev_b64 v[0:1], 12, v[0:1]
	v_lshl_add_u64 v[4:5], v[36:37], 0, v[0:1]
	flat_load_dwordx4 v[12:15], v[4:5]
	flat_load_dwordx4 v[8:11], v[4:5] offset:16
	flat_load_dwordx4 v[0:3], v[4:5] offset:2048
	s_nop 0
	flat_load_dwordx4 v[4:7], v[4:5] offset:2064
	v_cmp_lt_i32_e32 vcc, s30, v32
	s_and_b64 s[52:53], s[48:49], vcc
	v_readlane_b32 s41, v254, 34
	s_and_saveexec_b64 s[50:51], s[52:53]
	s_cbranch_execz .LBB0_2540
	v_lshlrev_b64 v[54:55], 2, v[176:177]
	v_lshl_add_u64 v[56:57], s[0:1], 0, v[54:55]
	v_mov_b32_e32 v53, v177
	v_lshl_add_u64 v[56:57], v[56:57], 0, v[52:53]
	s_brev_b32 s40, 31
	s_mov_b32 s41, -1
	v_lshl_add_u64 v[58:59], v[56:57], 0, s[40:41]
	s_mov_b32 s40, 0x800000
	s_mov_b32 s41, 0
	v_lshl_add_u64 v[60:61], v[58:59], 0, s[40:41]
	global_load_dwordx4 v[112:115], v[58:59], off
	global_load_dwordx4 v[116:119], v[58:59], off offset:16
	global_load_dwordx4 v[120:123], v[58:59], off offset:2048
	global_load_dwordx4 v[124:127], v[58:59], off offset:2064
	v_lshl_add_u64 v[58:59], v[60:61], 0, s[40:41]
	global_load_dwordx4 v[128:131], v[60:61], off
	global_load_dwordx4 v[132:135], v[60:61], off offset:16
	global_load_dwordx4 v[136:139], v[60:61], off offset:2048
	global_load_dwordx4 v[140:143], v[60:61], off offset:2064
	v_lshl_add_u64 v[60:61], v[58:59], 0, s[40:41]
	global_load_dwordx4 v[144:147], v[58:59], off
	global_load_dwordx4 v[148:151], v[58:59], off offset:16
	global_load_dwordx4 v[152:155], v[58:59], off offset:2048
	global_load_dwordx4 v[156:159], v[58:59], off offset:2064
	v_lshl_add_u64 v[58:59], v[60:61], 0, s[40:41]
	global_load_dwordx4 v[160:163], v[60:61], off
	global_load_dwordx4 v[164:167], v[60:61], off offset:16
	global_load_dwordx4 v[168:171], v[60:61], off offset:2048
	global_load_dwordx4 v[172:175], v[60:61], off offset:2064
	v_lshl_add_u64 v[60:61], v[58:59], 0, s[40:41]
	global_load_dwordx4 v[68:71], v[58:59], off
	global_load_dwordx4 v[72:75], v[58:59], off offset:16
	global_load_dwordx4 v[76:79], v[58:59], off offset:2048
	global_load_dwordx4 v[80:83], v[58:59], off offset:2064
	v_lshl_add_u64 v[58:59], v[60:61], 0, s[40:41]
	global_load_dwordx4 v[88:91], v[60:61], off
	global_load_dwordx4 v[92:95], v[60:61], off offset:16
	global_load_dwordx4 v[96:99], v[60:61], off offset:2048
	global_load_dwordx4 v[100:103], v[60:61], off offset:2064
	v_lshl_add_u64 v[60:61], v[58:59], 0, s[40:41]
	global_load_dwordx4 v[224:227], v[58:59], off
	global_load_dwordx4 v[228:231], v[58:59], off offset:16
	global_load_dwordx4 v[232:235], v[58:59], off offset:2048
	global_load_dwordx4 v[236:239], v[58:59], off offset:2064
	global_load_dwordx4 v[240:243], v[60:61], off
	global_load_dwordx4 v[244:247], v[60:61], off offset:16
	global_load_dwordx4 v[192:195], v[60:61], off offset:2048
	global_load_dwordx4 v[196:199], v[60:61], off offset:2064
	v_lshl_add_u64 v[54:55], v[36:37], 0, v[54:55]
	s_waitcnt vmcnt(0) lgkmcnt(0)
	v_pk_add_f32 v[28:29], v[28:29], v[112:113]
	v_pk_add_f32 v[30:31], v[30:31], v[114:115]
	v_pk_add_f32 v[24:25], v[24:25], v[116:117]
	v_pk_add_f32 v[26:27], v[26:27], v[118:119]
	v_pk_add_f32 v[16:17], v[16:17], v[120:121]
	v_pk_add_f32 v[18:19], v[18:19], v[122:123]
	v_pk_add_f32 v[20:21], v[20:21], v[124:125]
	v_pk_add_f32 v[22:23], v[22:23], v[126:127]
	v_pk_add_f32 v[28:29], v[28:29], v[128:129]
	v_pk_add_f32 v[30:31], v[30:31], v[130:131]
	v_pk_add_f32 v[24:25], v[24:25], v[132:133]
	v_pk_add_f32 v[26:27], v[26:27], v[134:135]
	v_pk_add_f32 v[16:17], v[16:17], v[136:137]
	v_pk_add_f32 v[18:19], v[18:19], v[138:139]
	v_pk_add_f32 v[20:21], v[20:21], v[140:141]
	v_pk_add_f32 v[22:23], v[22:23], v[142:143]
	v_pk_add_f32 v[28:29], v[28:29], v[144:145]
	v_pk_add_f32 v[30:31], v[30:31], v[146:147]
	v_pk_add_f32 v[24:25], v[24:25], v[148:149]
	v_pk_add_f32 v[26:27], v[26:27], v[150:151]
	v_pk_add_f32 v[16:17], v[16:17], v[152:153]
	v_pk_add_f32 v[18:19], v[18:19], v[154:155]
	v_pk_add_f32 v[20:21], v[20:21], v[156:157]
	v_pk_add_f32 v[22:23], v[22:23], v[158:159]
	v_pk_add_f32 v[28:29], v[28:29], v[160:161]
	v_pk_add_f32 v[30:31], v[30:31], v[162:163]
	v_pk_add_f32 v[24:25], v[24:25], v[164:165]
	v_pk_add_f32 v[26:27], v[26:27], v[166:167]
	v_pk_add_f32 v[16:17], v[16:17], v[168:169]
	v_pk_add_f32 v[18:19], v[18:19], v[170:171]
	v_pk_add_f32 v[20:21], v[20:21], v[172:173]
	v_pk_add_f32 v[22:23], v[22:23], v[174:175]
	v_pk_add_f32 v[28:29], v[28:29], v[68:69]
	v_pk_add_f32 v[30:31], v[30:31], v[70:71]
	v_pk_add_f32 v[24:25], v[24:25], v[72:73]
	v_pk_add_f32 v[26:27], v[26:27], v[74:75]
	v_pk_add_f32 v[16:17], v[16:17], v[76:77]
	v_pk_add_f32 v[18:19], v[18:19], v[78:79]
	v_pk_add_f32 v[20:21], v[20:21], v[80:81]
	v_pk_add_f32 v[22:23], v[22:23], v[82:83]
	v_pk_add_f32 v[28:29], v[28:29], v[88:89]
	v_pk_add_f32 v[30:31], v[30:31], v[90:91]
	v_pk_add_f32 v[24:25], v[24:25], v[92:93]
	v_pk_add_f32 v[26:27], v[26:27], v[94:95]
	v_pk_add_f32 v[16:17], v[16:17], v[96:97]
	v_pk_add_f32 v[18:19], v[18:19], v[98:99]
	v_pk_add_f32 v[20:21], v[20:21], v[100:101]
	v_pk_add_f32 v[22:23], v[22:23], v[102:103]
	v_pk_add_f32 v[28:29], v[28:29], v[224:225]
	v_pk_add_f32 v[30:31], v[30:31], v[226:227]
	v_pk_add_f32 v[24:25], v[24:25], v[228:229]
	v_pk_add_f32 v[26:27], v[26:27], v[230:231]
	v_pk_add_f32 v[16:17], v[16:17], v[232:233]
	v_pk_add_f32 v[18:19], v[18:19], v[234:235]
	v_pk_add_f32 v[20:21], v[20:21], v[236:237]
	v_pk_add_f32 v[22:23], v[22:23], v[238:239]
	v_pk_add_f32 v[28:29], v[28:29], v[240:241]
	v_pk_add_f32 v[30:31], v[30:31], v[242:243]
	v_pk_add_f32 v[24:25], v[24:25], v[244:245]
	v_pk_add_f32 v[26:27], v[26:27], v[246:247]
	v_pk_add_f32 v[16:17], v[16:17], v[192:193]
	v_pk_add_f32 v[18:19], v[18:19], v[194:195]
	v_pk_add_f32 v[20:21], v[20:21], v[196:197]
	v_pk_add_f32 v[22:23], v[22:23], v[198:199]
	global_store_dwordx4 v[54:55], v[28:31], off
	global_store_dwordx4 v[54:55], v[24:27], off offset:16
	global_store_dwordx4 v[54:55], v[16:19], off offset:2048
	global_store_dwordx4 v[54:55], v[20:23], off offset:2064
